# ring8 plus hand-scheduled mixer-A tile body and 3-deep K/V prefetch ring for mixer A
# speedup vs baseline: 1.0077x; 1.0077x over previous
; #define VSYNC() vb_sync(vc)
; template <int NS>
; DI void attn_item(const Params& p, int layer, char* smem, VBC& vc, int b, int hq, int qblk) {
;     ...
;     auto tile_ptrs = [&](int it, const u16*& kp, const u16*& vp) {
;         if (it < lat1 - lat0) { int kt = lat0 + it; kp = P + (size_t)(b * SEQ + kt * 64) * PC + kcol; vp = VT + kt * 64; }
;         else { int c = it - (lat1 - lat0); kp = P + (size_t)(NLAT + b * CTXL + c * 64) * PC + kcol; vp = VT + SEQ + c * 64; }
;     };
;     auto dma_tile = [&](int it, int st) {
;         const u16 *kp, *vp; tile_ptrs(it, kp, vp);
; #pragma unroll
;         for (int i = 0; i < 2; ++i) {
;             const int row = wave4 * 16 + i * 8 + drow;
;             const int chunk = dslot ^ ((row >> 1) & 7);
;             lds_u32* dk = (lds_u32*)(sK + st * 8192 + (wave4 * 16 + i * 8) * 64);
;             lds_u32* dv = (lds_u32*)(sK + st * 8192 + 4096 + (wave4 * 16 + i * 8) * 64);
;             __builtin_amdgcn_global_load_lds((const unsigned*)(kp + (size_t)row * PC + chunk * 8), dk, 16, 0, 0);
;             __builtin_amdgcn_global_load_lds((const unsigned*)(vp + (size_t)row * KVS + chunk * 8), dv, 16, 0, 0);
;         }
;     };
;     const int hs16 = ((h ^ ((r >> 1) & 7)) << 3);
;     const bf16x8 kones = __builtin_bit_cast(bf16x8, (uint4){0x00003F80u, 0u, 0u, 0u});
;     auto run_tiles = [&](const bool fast) {
;     dma_tile(0, 0);
;     asm volatile("s_waitcnt vmcnt(0)" ::: "memory");
;     VSYNC();
;     for (int it = 0; it < ntiles; ++it) {
;         const int buf = it & 1;
;         if (it + 1 < ntiles) dma_tile(it + 1, buf ^ 1);
.LBB0_1023:
	s_add_i32 s89, s90, 1
	s_cmp_lg_u32 s90, 0
	s_cbranch_scc1 .La_dma3
	s_mov_b32 s11, 1
	s_mov_b32 s12, 0x4000
	s_cmp_lt_i32 s11, s79
	s_cselect_b32 s0, s78, s86
	s_cselect_b32 s1, s76, s82
	s_cselect_b32 s7, s80, s83
	s_cselect_b32 s8, s81, s84
	s_add_i32 s0, s0, s11
	s_lshl_b32 s0, s0, 6
	s_add_i32 s9, s0, s1
	s_mov_b32 s1, s53
	s_lshl_b64 s[0:1], s[0:1], 1
	s_add_u32 s0, s7, s0
	s_addc_u32 s1, s8, s1
	s_mul_hi_i32 s7, s9, 0x1a80
	s_mulk_i32 s9, 0x1a80
	s_add_u32 s8, s64, s9
	s_addc_u32 s9, s65, s7
	s_add_i32 s7, s33, s12
	v_lshl_add_u32 v5, v187, 1, s7
	v_lshl_add_u64 v[2:3], s[8:9], 0, v[164:165]
	v_mov_b32_e32 v181, v1
	v_lshl_add_u64 v[2:3], v[2:3], 0, v[180:181]
	v_readfirstlane_b32 s10, v5
	v_add_u32_e32 v6, 0x2000, v5
	v_lshl_add_u64 v[2:3], v[2:3], 0, s[50:51]
	s_mov_b32 m0, s10
	v_readfirstlane_b32 s10, v6
	global_load_lds_dwordx4 v[2:3], off
	v_lshl_add_u64 v[2:3], s[0:1], 0, v[166:167]
	v_lshl_add_u64 v[2:3], v[2:3], 0, v[180:181]
	s_mov_b32 m0, s10
	v_lshl_add_u32 v5, v190, 1, s7
	global_load_lds_dwordx4 v[2:3], off
	v_lshl_add_u64 v[2:3], s[8:9], 0, v[168:169]
	v_mov_b32_e32 v183, v1
	v_readfirstlane_b32 s7, v5
	v_add_u32_e32 v6, 0x2000, v5
	v_lshl_add_u64 v[2:3], v[2:3], 0, v[182:183]
	v_lshl_add_u64 v[2:3], v[2:3], 0, s[50:51]
	s_mov_b32 m0, s7
	s_nop 0
	global_load_lds_dwordx4 v[2:3], off
	v_lshl_add_u64 v[2:3], s[0:1], 0, v[170:171]
	v_readfirstlane_b32 s0, v6
	v_lshl_add_u64 v[2:3], v[2:3], 0, v[182:183]
	s_mov_b32 m0, s0
	s_nop 0
	global_load_lds_dwordx4 v[2:3], off
	s_mov_b32 s11, 2
	s_mov_b32 s12, 0x8000
	s_cmp_lt_i32 s11, s79
	s_cselect_b32 s0, s78, s86
	s_cselect_b32 s1, s76, s82
	s_cselect_b32 s7, s80, s83
	s_cselect_b32 s8, s81, s84
	s_add_i32 s0, s0, s11
	s_lshl_b32 s0, s0, 6
	s_add_i32 s9, s0, s1
	s_mov_b32 s1, s53
	s_lshl_b64 s[0:1], s[0:1], 1
	s_add_u32 s0, s7, s0
	s_addc_u32 s1, s8, s1
	s_mul_hi_i32 s7, s9, 0x1a80
	s_mulk_i32 s9, 0x1a80
	s_add_u32 s8, s64, s9
	s_addc_u32 s9, s65, s7
	s_add_i32 s7, s33, s12
	v_lshl_add_u32 v5, v187, 1, s7
	v_lshl_add_u64 v[2:3], s[8:9], 0, v[164:165]
	v_mov_b32_e32 v181, v1
	v_lshl_add_u64 v[2:3], v[2:3], 0, v[180:181]
	v_readfirstlane_b32 s10, v5
	v_add_u32_e32 v6, 0x2000, v5
	v_lshl_add_u64 v[2:3], v[2:3], 0, s[50:51]
	s_mov_b32 m0, s10
	v_readfirstlane_b32 s10, v6
	global_load_lds_dwordx4 v[2:3], off
	v_lshl_add_u64 v[2:3], s[0:1], 0, v[166:167]
	v_lshl_add_u64 v[2:3], v[2:3], 0, v[180:181]
	s_mov_b32 m0, s10
	v_lshl_add_u32 v5, v190, 1, s7
	global_load_lds_dwordx4 v[2:3], off
	v_lshl_add_u64 v[2:3], s[8:9], 0, v[168:169]
	v_mov_b32_e32 v183, v1
	v_readfirstlane_b32 s7, v5
	v_add_u32_e32 v6, 0x2000, v5
	v_lshl_add_u64 v[2:3], v[2:3], 0, v[182:183]
	v_lshl_add_u64 v[2:3], v[2:3], 0, s[50:51]
	s_mov_b32 m0, s7
	s_nop 0
	global_load_lds_dwordx4 v[2:3], off
	v_lshl_add_u64 v[2:3], s[0:1], 0, v[170:171]
	v_readfirstlane_b32 s0, v6
	v_lshl_add_u64 v[2:3], v[2:3], 0, v[182:183]
	s_mov_b32 m0, s0
	s_nop 0
	global_load_lds_dwordx4 v[2:3], off
.La_dma3:
	s_add_i32 s11, s90, 3
	s_cmp_lt_i32 s11, s87
	s_cbranch_scc0 .La_nodma
	s_and_b32 s12, s11, 3
	s_lshl_b32 s12, s12, 14
	s_cmp_lt_i32 s11, s79
	s_cselect_b32 s0, s78, s86
	s_cselect_b32 s1, s76, s82
	s_cselect_b32 s7, s80, s83
	s_cselect_b32 s8, s81, s84
	s_add_i32 s0, s0, s11
	s_lshl_b32 s0, s0, 6
	s_add_i32 s9, s0, s1
	s_mov_b32 s1, s53
	s_lshl_b64 s[0:1], s[0:1], 1
	s_add_u32 s0, s7, s0
	s_addc_u32 s1, s8, s1
	s_mul_hi_i32 s7, s9, 0x1a80
	s_mulk_i32 s9, 0x1a80
	s_add_u32 s8, s64, s9
	s_addc_u32 s9, s65, s7
	s_add_i32 s7, s33, s12
	v_lshl_add_u32 v5, v187, 1, s7
	v_lshl_add_u64 v[2:3], s[8:9], 0, v[164:165]
	v_mov_b32_e32 v181, v1
	v_lshl_add_u64 v[2:3], v[2:3], 0, v[180:181]
	v_readfirstlane_b32 s10, v5
	v_add_u32_e32 v6, 0x2000, v5
	v_lshl_add_u64 v[2:3], v[2:3], 0, s[50:51]
	s_mov_b32 m0, s10
	v_readfirstlane_b32 s10, v6
	global_load_lds_dwordx4 v[2:3], off
	v_lshl_add_u64 v[2:3], s[0:1], 0, v[166:167]
	v_lshl_add_u64 v[2:3], v[2:3], 0, v[180:181]
	s_mov_b32 m0, s10
	v_lshl_add_u32 v5, v190, 1, s7
	global_load_lds_dwordx4 v[2:3], off
	v_lshl_add_u64 v[2:3], s[8:9], 0, v[168:169]
	v_mov_b32_e32 v183, v1
	v_readfirstlane_b32 s7, v5
	v_add_u32_e32 v6, 0x2000, v5
	v_lshl_add_u64 v[2:3], v[2:3], 0, v[182:183]
	v_lshl_add_u64 v[2:3], v[2:3], 0, s[50:51]
	s_mov_b32 m0, s7
	s_nop 0
	global_load_lds_dwordx4 v[2:3], off
	v_lshl_add_u64 v[2:3], s[0:1], 0, v[170:171]
	v_readfirstlane_b32 s0, v6
	v_lshl_add_u64 v[2:3], v[2:3], 0, v[182:183]
	s_mov_b32 m0, s0
	s_nop 0
	global_load_lds_dwordx4 v[2:3], off
.La_nodma:
	s_and_b32 s7, s90, 3
	s_lshl_b32 s7, s7, 13
.LBB0_1025:
	s_cmp_eq_u32 s90, 0
	s_cbranch_scc1 .Lorig_1025A
	s_and_b64 vcc, exec, s[62:63]
	s_cbranch_vccnz .Lfa_tile

; DI int lane_id() { int l; asm volatile("v_mbcnt_lo_u32_b32 %0, -1, 0\n\tv_mbcnt_hi_u32_b32 %0, -1, %0" : "=v"(l)); return l; }
; #define VSYNC() vb_sync(vc)
; DI void vb_sync(VBC& vc) {
;     vc.gen += 4u;
;     __builtin_amdgcn_fence(__ATOMIC_RELEASE, "workgroup");
;     asm volatile("s_waitcnt lgkmcnt(0)" ::: "memory");
;     if (lane_id() == 0) __hip_atomic_fetch_add(vc.cnt, 1u, __ATOMIC_RELAXED, __HIP_MEMORY_SCOPE_WORKGROUP);
;     while (__hip_atomic_load(vc.cnt, __ATOMIC_RELAXED, __HIP_MEMORY_SCOPE_WORKGROUP) < vc.gen) __builtin_amdgcn_s_sleep(1);
;     __builtin_amdgcn_fence(__ATOMIC_ACQUIRE, "workgroup");
; }
; template <int NS>
; DI void attn_item(const Params& p, int layer, char* smem, VBC& vc, int b, int hq, int qblk) {
;     ...
;         asm volatile("s_waitcnt vmcnt(0)" ::: "memory");
;         VSYNC();
.Lfa_tail:
	s_sub_i32 s0, s87, s90
	s_cmp_ge_i32 s0, 4
	s_cbranch_scc1 .La_w8
	s_cmp_eq_u32 s0, 3
	s_cbranch_scc1 .La_w4
	s_waitcnt vmcnt(0)
	s_branch .La_wd
.La_w8:
	s_waitcnt vmcnt(8)
	s_branch .La_wd
.La_w4:
	s_waitcnt vmcnt(4)
.La_wd:
	s_waitcnt lgkmcnt(0)
	v_mbcnt_lo_u32_b32 v0, -1, 0
	v_mbcnt_hi_u32_b32 v0, -1, v0
	s_nop 0
	v_cmp_eq_u32_e32 vcc, 0, v0
	s_and_saveexec_b64 s[0:1], vcc
	s_cbranch_execz .LBB0_1038
	s_mov_b64 s[6:7], exec
	v_mbcnt_lo_u32_b32 v0, s6, 0
	v_mbcnt_hi_u32_b32 v0, s7, v0
	v_cmp_eq_u32_e32 vcc, 0, v0
	s_and_b64 s[8:9], exec, vcc
	s_mov_b64 exec, s[8:9]
	s_bcnt1_i32_b64 s6, s[6:7]
	v_mov_b32_e32 v0, s35
	v_mov_b32_e32 v2, s6
	ds_add_u32 v0, v2

; #define MFMA(a, b, c) __builtin_amdgcn_mfma_f32_32x32x16_bf16((a), (b), (c), 0, 0, 0)
; DI int crow(int e, int h) { return (e & 3) + 8 * (e >> 2) + 4 * h; }
; template <int NS>
; DI void attn_item(const Params& p, int layer, char* smem, VBC& vc, int b, int hq, int qblk) {
;     ...
;         auto qk = [&](const int m, f32x16 (&s)[2]) {
; #pragma unroll
;             for (int kt2 = 0; kt2 < 2; ++kt2)
; #pragma unroll
;                 for (int e = 0; e < 16; ++e) s[kt2][e] = 0.f;
;             __builtin_amdgcn_s_setprio(1);
; #pragma unroll
;             for (int ks = 0; ks < NKS; ++ks)
; #pragma unroll
;                 for (int kt2 = 0; kt2 < 2; ++kt2) s[kt2] = MFMA(ld8(cK + (kt2 * 32 + r) * 64 + (((m * DQK + ks * 16)) ^ hs16)), qf[m][ks], s[kt2]);
; #pragma unroll
;             for (int kt2 = 0; kt2 < 2; ++kt2) { uint4 qa4 = {qaug[m], 0u, 0u, 0u}; s[kt2] = MFMA(kones, __builtin_bit_cast(bf16x8, qa4), s[kt2]); }
;             __builtin_amdgcn_s_setprio(0);
;         };
;         auto softmax = [&](const int m, f32x16 (&s)[2], bf16x8 (&pf)[2][2]) {
;             const bool fixed = fast && it > 0;
;             if (NS == 1 && is_lat) {
; #pragma unroll
;                 for (int kt2 = 0; kt2 < 2; ++kt2)
; #pragma unroll
;                     for (int e = 0; e < 16; ++e) {
;                         int d = kpos0 + kt2 * 32 + crow(e, h) - qpos;
;                         if (d > 128 || d < -128) s[kt2][e] = -1e30f;
;                     }
;             }
.Lfa_tile:
	v_lshl_add_u32 v2, s7, 1, v244
	v_lshl_add_u32 v6, v189, 1, v2
	v_lshl_add_u32 v5, v192, 1, v2
	ds_read_b128 v[96:99], v6
	ds_read_b128 v[100:103], v6 offset:4096
	v_lshl_add_u32 v7, v193, 1, v2
	ds_read_b128 v[104:107], v5
	ds_read_b128 v[108:111], v5 offset:4096
	v_lshl_add_u32 v8, v194, 1, v2
	ds_read_b128 v[112:115], v7
	ds_read_b128 v[116:119], v7 offset:4096
	ds_read_b128 v[120:123], v8
	ds_read_b128 v[124:127], v8 offset:4096
	v_mov_b32_e32 v2, 0
	v_mov_b32_e32 v3, 0
	v_mov_b32_e32 v12, s52
	v_mov_b32_e32 v13, 0
	v_mov_b32_e32 v14, 0
	v_mov_b32_e32 v15, 0
	s_waitcnt lgkmcnt(7)
	v_mfma_f32_32x32x16_bf16 v[64:79], v[96:99], v[144:147], 0
	s_waitcnt lgkmcnt(6)
	v_mfma_f32_32x32x16_bf16 v[48:63], v[100:103], v[144:147], 0
	s_waitcnt lgkmcnt(5)
	v_mfma_f32_32x32x16_bf16 v[64:79], v[104:107], v[148:151], v[64:79]
	s_waitcnt lgkmcnt(4)
	v_mfma_f32_32x32x16_bf16 v[48:63], v[108:111], v[148:151], v[48:63]
	ds_read_b128 v[96:99], v6 offset:8192
	ds_read_b128 v[100:103], v6 offset:12288
	ds_read_b128 v[104:107], v5 offset:8192
	ds_read_b128 v[108:111], v5 offset:12288
	s_waitcnt lgkmcnt(7)
	v_mfma_f32_32x32x16_bf16 v[64:79], v[112:115], v[152:155], v[64:79]
	s_waitcnt lgkmcnt(6)
	v_mfma_f32_32x32x16_bf16 v[48:63], v[116:119], v[152:155], v[48:63]
	s_waitcnt lgkmcnt(5)
	v_mfma_f32_32x32x16_bf16 v[64:79], v[120:123], v[156:159], v[64:79]
	s_waitcnt lgkmcnt(4)
	v_mfma_f32_32x32x16_bf16 v[48:63], v[124:127], v[156:159], v[48:63]
	v_mfma_f32_32x32x16_bf16 v[64:79], v[12:15], v[0:3], v[64:79]
	v_mfma_f32_32x32x16_bf16 v[48:63], v[12:15], v[0:3], v[48:63]
	ds_read_b128 v[112:115], v7 offset:8192
	ds_read_b128 v[116:119], v7 offset:12288
	ds_read_b128 v[120:123], v8 offset:8192
	ds_read_b128 v[124:127], v8 offset:12288
	s_add_i32 s0, s90, s78
	v_lshl_or_b32 v9, s0, 6, v185
	v_add_u32_e32 v9, v195, v9
	s_nop 3
	s_cmp_lt_i32 s90, s79
	s_cbranch_scc0 .Lfa_nomask
	v_add_u32_e32 v80, 0, v9
	v_add_u32_e32 v81, 1, v9
	v_add_u32_e32 v82, 2, v9
	v_add_u32_e32 v83, 3, v9
	v_add_u32_e32 v84, 8, v9
	v_add_u32_e32 v85, 9, v9
	v_add_u32_e32 v86, 10, v9
	v_add_u32_e32 v87, 11, v9
	v_add_u32_e32 v88, 16, v9
	v_add_u32_e32 v89, 17, v9
	v_add_u32_e32 v90, 18, v9
	v_add_u32_e32 v91, 19, v9
	v_add_u32_e32 v92, 24, v9
	v_add_u32_e32 v93, 25, v9
	v_add_u32_e32 v94, 26, v9
	v_add_u32_e32 v95, 27, v9
	v_add_u32_e32 v128, 32, v9
	v_add_u32_e32 v129, 33, v9
	v_add_u32_e32 v130, 34, v9
	v_add_u32_e32 v131, 35, v9
	v_add_u32_e32 v132, 40, v9
	v_add_u32_e32 v133, 41, v9
	v_add_u32_e32 v134, 42, v9
	v_add_u32_e32 v135, 43, v9
	v_add_u32_e32 v136, 48, v9
	v_add_u32_e32 v137, 49, v9
	v_add_u32_e32 v138, 50, v9
	v_add_u32_e32 v139, 51, v9
	v_add_u32_e32 v140, 56, v9
	v_add_u32_e32 v141, 57, v9
	v_add_u32_e32 v142, 58, v9
	v_add_u32_e32 v143, 59, v9
	v_cmp_lt_u32_e64 s[0:1], s70, v80
	v_cmp_lt_u32_e64 s[6:7], s70, v81
	v_cmp_lt_u32_e64 s[8:9], s70, v82
	v_cndmask_b32_e64 v64, v239, v64, s[0:1]
	v_cmp_lt_u32_e64 s[0:1], s70, v83
	v_cndmask_b32_e64 v65, v239, v65, s[6:7]
	v_cmp_lt_u32_e64 s[6:7], s70, v84
	v_cndmask_b32_e64 v66, v239, v66, s[8:9]
	v_cmp_lt_u32_e64 s[8:9], s70, v85
	v_cndmask_b32_e64 v67, v239, v67, s[0:1]
	v_cmp_lt_u32_e64 s[0:1], s70, v86
	v_cndmask_b32_e64 v68, v239, v68, s[6:7]
	v_cmp_lt_u32_e64 s[6:7], s70, v87
	v_cndmask_b32_e64 v69, v239, v69, s[8:9]
	v_cmp_lt_u32_e64 s[8:9], s70, v88
	v_cndmask_b32_e64 v70, v239, v70, s[0:1]
	v_cmp_lt_u32_e64 s[0:1], s70, v89
	v_cndmask_b32_e64 v71, v239, v71, s[6:7]
	v_cmp_lt_u32_e64 s[6:7], s70, v90
	v_cndmask_b32_e64 v72, v239, v72, s[8:9]
	v_cmp_lt_u32_e64 s[8:9], s70, v91
	v_cndmask_b32_e64 v73, v239, v73, s[0:1]
	v_cmp_lt_u32_e64 s[0:1], s70, v92
	v_cndmask_b32_e64 v74, v239, v74, s[6:7]
	v_cmp_lt_u32_e64 s[6:7], s70, v93
	v_cndmask_b32_e64 v75, v239, v75, s[8:9]
	v_cmp_lt_u32_e64 s[8:9], s70, v94
	v_cndmask_b32_e64 v76, v239, v76, s[0:1]
	v_cmp_lt_u32_e64 s[0:1], s70, v95
	v_cndmask_b32_e64 v77, v239, v77, s[6:7]
	v_cmp_lt_u32_e64 s[6:7], s70, v128
	v_cndmask_b32_e64 v78, v239, v78, s[8:9]
	v_cmp_lt_u32_e64 s[8:9], s70, v129
	v_cndmask_b32_e64 v79, v239, v79, s[0:1]
	v_cmp_lt_u32_e64 s[0:1], s70, v130
	v_cndmask_b32_e64 v48, v239, v48, s[6:7]
	v_cmp_lt_u32_e64 s[6:7], s70, v131
	v_cndmask_b32_e64 v49, v239, v49, s[8:9]
	v_cmp_lt_u32_e64 s[8:9], s70, v132
	v_cndmask_b32_e64 v50, v239, v50, s[0:1]
	v_cmp_lt_u32_e64 s[0:1], s70, v133
	v_cndmask_b32_e64 v51, v239, v51, s[6:7]
	v_cmp_lt_u32_e64 s[6:7], s70, v134
	v_cndmask_b32_e64 v52, v239, v52, s[8:9]
	v_cmp_lt_u32_e64 s[8:9], s70, v135
	v_cndmask_b32_e64 v53, v239, v53, s[0:1]
	v_cmp_lt_u32_e64 s[0:1], s70, v136
	v_cndmask_b32_e64 v54, v239, v54, s[6:7]
	v_cmp_lt_u32_e64 s[6:7], s70, v137
	v_cndmask_b32_e64 v55, v239, v55, s[8:9]
	v_cmp_lt_u32_e64 s[8:9], s70, v138
	v_cndmask_b32_e64 v56, v239, v56, s[0:1]
	v_cmp_lt_u32_e64 s[0:1], s70, v139
	v_cndmask_b32_e64 v57, v239, v57, s[6:7]
	v_cmp_lt_u32_e64 s[6:7], s70, v140
	v_cndmask_b32_e64 v58, v239, v58, s[8:9]
	v_cmp_lt_u32_e64 s[8:9], s70, v141
	v_cndmask_b32_e64 v59, v239, v59, s[0:1]
	v_cmp_lt_u32_e64 s[0:1], s70, v142
	v_cndmask_b32_e64 v60, v239, v60, s[6:7]
	v_cmp_lt_u32_e64 s[6:7], s70, v143
	v_cndmask_b32_e64 v61, v239, v61, s[8:9]
	s_nop 0
	v_cndmask_b32_e64 v62, v239, v62, s[0:1]
	v_cndmask_b32_e64 v63, v239, v63, s[6:7]
; #define MFMA(a, b, c) __builtin_amdgcn_mfma_f32_32x32x16_bf16((a), (b), (c), 0, 0, 0)
; template <int NS>
; DI void attn_item(const Params& p, int layer, char* smem, VBC& vc, int b, int hq, int qblk) {
;     ...
;             if (fixed) {
;                 float ls = 0.f;
; #pragma unroll
;                 for (int kt2 = 0; kt2 < 2; ++kt2)
; #pragma unroll
;                     for (int e = 0; e < 16; ++e) { const float pv = __builtin_amdgcn_exp2f(s[kt2][e]); s[kt2][e] = pv; ls += pv; }
;                 lrun[m] += ls;
;             } else {
;     ...
; #pragma unroll
;             for (int kt2 = 0; kt2 < 2; ++kt2) { pf[kt2][0] = pack8(s[kt2], 0); pf[kt2][1] = pack8(s[kt2], 1); }
;         };
;         auto pvm = [&](const int m, const bf16x8 (&pf)[2][2]) {
;             __builtin_amdgcn_s_setprio(1);
; #pragma unroll
;             for (int kk = 0; kk < 4; ++kk)
; #pragma unroll
;                 for (int dvt = 0; dvt < 2; ++dvt) O[m][dvt] = MFMA(ld8(cV + (dvt * 32 + r) * 64 + ((kk * 16) ^ hs16)), pf[kk >> 1][kk & 1], O[m][dvt]);
;             __builtin_amdgcn_s_setprio(0);
;         };
.Lfa_nomask:
	v_exp_f32_e32 v64, v64
	v_exp_f32_e32 v65, v65
	v_exp_f32_e32 v66, v66
	v_exp_f32_e32 v67, v67
	v_exp_f32_e32 v68, v68
	v_exp_f32_e32 v69, v69
	v_pk_add_f32 v[10:11], v[64:65], v[66:67]
	v_exp_f32_e32 v70, v70
	v_exp_f32_e32 v71, v71
	v_pk_add_f32 v[10:11], v[10:11], v[68:69]
	v_exp_f32_e32 v72, v72
	v_exp_f32_e32 v73, v73
	v_pk_add_f32 v[10:11], v[10:11], v[70:71]
	v_exp_f32_e32 v74, v74
	v_exp_f32_e32 v75, v75
	v_pk_add_f32 v[10:11], v[10:11], v[72:73]
	v_exp_f32_e32 v76, v76
	v_exp_f32_e32 v77, v77
	v_pk_add_f32 v[10:11], v[10:11], v[74:75]
	v_exp_f32_e32 v78, v78
	v_exp_f32_e32 v79, v79
	v_pk_add_f32 v[10:11], v[10:11], v[76:77]
	v_exp_f32_e32 v48, v48
	v_exp_f32_e32 v49, v49
	v_pk_add_f32 v[10:11], v[10:11], v[78:79]
	v_exp_f32_e32 v50, v50
	v_exp_f32_e32 v51, v51
	v_pk_add_f32 v[10:11], v[10:11], v[48:49]
	v_exp_f32_e32 v52, v52
	v_exp_f32_e32 v53, v53
	v_pk_add_f32 v[10:11], v[10:11], v[50:51]
	v_exp_f32_e32 v54, v54
	v_exp_f32_e32 v55, v55
	v_pk_add_f32 v[10:11], v[10:11], v[52:53]
	v_exp_f32_e32 v56, v56
	v_exp_f32_e32 v57, v57
	v_pk_add_f32 v[10:11], v[10:11], v[54:55]
	v_exp_f32_e32 v58, v58
	v_exp_f32_e32 v59, v59
	v_pk_add_f32 v[10:11], v[10:11], v[56:57]
	v_exp_f32_e32 v60, v60
	v_exp_f32_e32 v61, v61
	v_pk_add_f32 v[10:11], v[10:11], v[58:59]
	v_exp_f32_e32 v62, v62
	v_exp_f32_e32 v63, v63
	v_pk_add_f32 v[10:11], v[10:11], v[60:61]
	v_mov_b32_e32 v184, v245
	v_pk_add_f32 v[10:11], v[10:11], v[62:63]
	v_cvt_pk_bf16_f32 v64, v64, v65
	v_cvt_pk_bf16_f32 v65, v66, v67
	v_cvt_pk_bf16_f32 v66, v68, v69
	v_cvt_pk_bf16_f32 v67, v70, v71
	v_cvt_pk_bf16_f32 v68, v72, v73
	v_cvt_pk_bf16_f32 v69, v74, v75
	v_cvt_pk_bf16_f32 v70, v76, v77
	v_cvt_pk_bf16_f32 v71, v78, v79
	v_cvt_pk_bf16_f32 v48, v48, v49
	v_cvt_pk_bf16_f32 v49, v50, v51
	v_cvt_pk_bf16_f32 v50, v52, v53
	v_cvt_pk_bf16_f32 v51, v54, v55
	v_cvt_pk_bf16_f32 v52, v56, v57
	v_cvt_pk_bf16_f32 v53, v58, v59
	v_cvt_pk_bf16_f32 v54, v60, v61
	v_cvt_pk_bf16_f32 v55, v62, v63
	v_add_f32_e32 v10, v10, v11
	v_add_f32_e32 v3, v4, v10
	v_mov_b32_e32 v181, v0
	s_waitcnt lgkmcnt(7)
	v_mfma_f32_32x32x16_bf16 v[32:47], v[96:99], v[64:67], v[32:47]
	s_waitcnt lgkmcnt(6)
	v_mfma_f32_32x32x16_bf16 v[16:31], v[100:103], v[64:67], v[16:31]
	s_waitcnt lgkmcnt(5)
	v_mfma_f32_32x32x16_bf16 v[32:47], v[104:107], v[68:71], v[32:47]
	s_waitcnt lgkmcnt(4)
	v_mfma_f32_32x32x16_bf16 v[16:31], v[108:111], v[68:71], v[16:31]
	s_waitcnt lgkmcnt(3)
	v_mfma_f32_32x32x16_bf16 v[32:47], v[112:115], v[48:51], v[32:47]
	s_waitcnt lgkmcnt(2)
	v_mfma_f32_32x32x16_bf16 v[16:31], v[116:119], v[48:51], v[16:31]
	s_waitcnt lgkmcnt(1)
	v_mfma_f32_32x32x16_bf16 v[32:47], v[120:123], v[52:55], v[32:47]
	s_waitcnt lgkmcnt(0)
	v_mfma_f32_32x32x16_bf16 v[16:31], v[124:127], v[52:55], v[16:31]
	s_branch .Lfa_tail
